# KIND1 tile loop unrolled by the 3 ring slots: per-slot fragment-read addresses held for the unit, five vector adds per tile removed
# baseline (speedup 1.0000x reference)
; DI int otid() { int t = threadIdx.x; asm volatile("" : "+v"(t)); return t; }
; DI int crow(int reg, int h) { return (reg & 3) + 8 * (reg >> 2) + 4 * h; }
; template <int KIND>
; DI void attn_unit(const Params& p, int l, int b, int head, int qt, int qcol, int kcol, int vfeat, int gcol, int mixcol,
;                   int t1, int n1, int t2, int n2, char* smem) {
;     const int tid = otid(), lane = tid & 63, wave = tid >> 6, r = lane & 31, h = lane >> 5;
;     const int tq = qt * 128 + 32 * wave + r;
;     const size_t qrow = (size_t)b * TPB + tq;
;     const bf16_t* kbase = p.qkv + ((size_t)(kcol >> 6) * NTOK + (size_t)b * TPB) * 64;
;     const bf16_t* vbase = p.vT + ((size_t)b * 12 + (vfeat >> 6)) * 36 * 4096;
;     const int nt = n1 + n2;
;     bf16x8 qf[4];
;     {
;         const bf16_t* qp = p.qkv + ((size_t)(qcol >> 6) * NTOK + qrow) * 64 + 8 * h;
; #pragma unroll
;         for (int s = 0; s < 4; ++s) qf[s] = *(const bf16x8*)(qp + 16 * s);
;     }
;     int nrow = 0, r0w = 0, qc = 0, c0 = 0;
;     if (KIND == 2) {
;         nrow = 2 * qt + (wave >> 1); r0w = min(max(nrow - 4, 0), 24);
;         qc = 32 * (wave & 1) + r; c0 = min(max(qc - 8, 0), 48);
;         float* bias = (float*)(smem + ATT_BIAS);
;         for (int i = tid; i < 15 * 32; i += NTHREADS) { const int rr = i >> 5, cc = i & 31; bias[i] = cc < 31 ? p.rpb[((size_t)l * 6 + head) * 465 + rr * 31 + cc] * LOG2E : -INFINITY; }
;     }
;     int bcol[2][16];
;     if (KIND == 2) {
; #pragma unroll
;         for (int t = 0; t < 2; ++t)
; #pragma unroll
;             for (int e = 0; e < 16; ++e) {
;                 const int kc = 32 * t + crow(e, h);
;                 bcol[t][e] = ((unsigned)(kc - c0) < 16u) ? (kc - qc + 15) * 4 : 31 * 4;
;             }
;     }
;     f32x16 O0[2], O1[2];
; #pragma unroll
;     for (int t = 0; t < 2; ++t)
; #pragma unroll
;         for (int e = 0; e < 16; ++e) { O0[t][e] = 0.f; O1[t][e] = 0.f; }
;     float l0 = 0.f, l1 = 0.f;
;     const float zb = p.lam[8 + l * 4 + ((KIND == 1 && qcol >= 2048) ? 3 : KIND)];
;     f32x16 cz;
; #pragma unroll
;     for (int e = 0; e < 16; ++e) cz[e] = -zb;
;     const int kvoff = (8 * wave + (lane >> 3)) * 64 + (((lane & 7) ^ (((wave & 1) << 2) | (lane >> 4))) << 3);
;     const int xr = (r >> 1) & 7;
;     __syncthreads();
;     KV_ISSUE(t1, 0);
;     if (nt > 1) KV_ISSUE((1 < n1) ? t1 + 1 : t2 + (1 - n1), 1);
.LBB0_103:
	s_lshr_b32 s4, s4, 6
	s_lshl_b32 s6, s29, 7
	s_mul_i32 s29, s35, 0x900
	s_mulk_i32 s4, 0x4800
	s_mul_hi_i32 s7, s35, 0x900
	s_add_u32 s52, s29, s4
	s_addc_u32 s53, s7, 0
	s_lshl_b64 s[52:53], s[52:53], 7
	s_mul_i32 s56, s35, 12
	s_lshr_b32 s45, s45, 6
	s_mul_hi_i32 s47, s35, 12
	s_add_u32 s56, s56, s45
	v_mov_b32_e32 v7, v200
	s_addc_u32 s47, s47, 0
	s_load_dwordx4 s[40:43], s[0:1], 0xc0
	s_load_dwordx2 s[50:51], s[0:1], 0xf8
	v_ashrrev_i32_e32 v2, 6, v7
	s_mul_i32 s47, s47, 0x48000
	s_mul_hi_u32 s57, s56, 0x48000
	s_mul_i32 s58, s56, 0x48000
	s_lshr_b32 s56, s34, 6
	v_and_b32_e32 v6, 31, v7
	v_lshl_add_u32 v0, v2, 5, s6
	s_add_i32 s47, s57, s47
	s_mulk_i32 s56, 0x4800
	v_or_b32_e32 v0, v0, v6
	s_add_u32 s56, s29, s56
	v_ashrrev_i32_e32 v1, 31, v0
	s_addc_u32 s57, s7, 0
	v_lshl_add_u64 v[0:1], s[56:57], 0, v[0:1]
	s_waitcnt lgkmcnt(0)
	s_add_u32 s56, s40, s52
	s_addc_u32 s57, s41, s53
	s_cmpk_gt_u32 s34, 0x7ff
	s_cselect_b32 s34, 3, 1
	s_add_u32 s52, s34, s48
	s_addc_u32 s53, 0, s49
	v_bfe_u32 v102, v7, 5, 1
	v_lshlrev_b64 v[0:1], 7, v[0:1]
	s_lshl_b64 s[52:53], s[52:53], 2
	v_lshl_add_u64 v[0:1], s[40:41], 0, v[0:1]
	v_lshlrev_b32_e32 v192, 4, v102
	s_add_u32 s50, s50, s52
	v_lshl_add_u64 v[0:1], v[0:1], 0, v[192:193]
	s_addc_u32 s51, s51, s53
	global_load_dwordx4 v[92:95], v[0:1], off
	global_load_dwordx4 v[88:91], v[0:1], off offset:32
	global_load_dwordx4 v[84:87], v[0:1], off offset:64
	global_load_dwordx4 v[80:83], v[0:1], off offset:96
	v_lshlrev_b32_e32 v1, 3, v7
	global_load_dword v0, v193, s[50:51] offset:32
	s_movk_i32 s50, 0x1c0
	v_bfe_u32 v3, v7, 4, 2
	s_add_u32 s52, s42, s58
	s_addc_u32 s47, s43, s47
	s_lshl_b32 s46, s46, 13
	v_lshl_add_u32 v100, v7, 4, 32
	v_lshrrev_b32_e32 v12, 1, v7
	v_bfe_u32 v13, v7, 1, 3
	s_barrier
	s_mov_b32 s5, s75
	v_lshlrev_b32_e32 v105, 7, v6
	v_mov_b32_e32 v104, 0
	s_mov_b32 s34, 2
	v_add_u32_e32 v108, 32, v105
	v_mov_b32_e32 v32, 0
	v_mov_b32_e32 v33, v104
	v_mov_b32_e32 v34, v104
	v_mov_b32_e32 v35, v104
	v_mov_b32_e32 v36, v104
	v_mov_b32_e32 v37, v104
	v_mov_b32_e32 v38, v104
	v_mov_b32_e32 v39, v104
	v_mov_b32_e32 v40, v104
	v_mov_b32_e32 v41, v104
	v_mov_b32_e32 v42, v104
	v_mov_b32_e32 v43, v104
	v_mov_b32_e32 v44, v104
	v_mov_b32_e32 v45, v104
	v_mov_b32_e32 v46, v104
	v_mov_b32_e32 v47, v104
	v_mov_b32_e32 v6, v104
	v_mov_b32_e32 v14, v104
	v_mov_b32_e32 v15, v104
	s_waitcnt vmcnt(0)
	v_xor_b32_e32 v16, 0x80000000, v0
	v_lshlrev_b32_e32 v0, 9, v2
	v_lshlrev_b32_e32 v2, 2, v2
	v_and_or_b32 v0, v1, s50, v0
	v_and_b32_e32 v1, 7, v7
	v_and_b32_e32 v2, 4, v2
	v_bitop3_b32 v1, v2, v1, v3 bitop3:0x36
	v_lshl_or_b32 v0, v1, 3, v0
	s_add_u32 s50, s56, s46
	v_ashrrev_i32_e32 v1, 31, v0
	s_addc_u32 s51, s57, 0
	v_lshlrev_b64 v[0:1], 1, v[0:1]
	v_lshl_add_u64 v[4:5], s[50:51], 0, v[0:1]
	s_add_u32 s50, s52, s46
	s_addc_u32 s51, s47, 0
	v_readfirstlane_b32 s47, v100
	v_add_u32_e32 v7, 0x1000, v100
	s_mov_b32 m0, s47
	v_readfirstlane_b32 s47, v7
	v_add_u32_e32 v7, 0x2000, v100
	global_load_lds_dwordx4 v[4:5], off
	v_lshl_add_u64 v[8:9], v[4:5], 0, s[26:27]
	s_mov_b32 m0, s47
	v_readfirstlane_b32 s47, v7
	v_add_u32_e32 v7, 0x3000, v100
	v_lshl_add_u64 v[2:3], s[50:51], 0, v[0:1]
	global_load_lds_dwordx4 v[8:9], off
	s_mov_b32 m0, s47
	v_readfirstlane_b32 s47, v7
	v_add_u32_e32 v7, 0x4000, v100
	global_load_lds_dwordx4 v[2:3], off
	v_lshl_add_u64 v[8:9], v[2:3], 0, s[26:27]
	s_mov_b32 m0, s47
	v_readfirstlane_b32 s47, v7
	v_add_u32_e32 v7, 0x5000, v100
	global_load_lds_dwordx4 v[8:9], off
	v_lshl_add_u64 v[8:9], v[4:5], 0, s[16:17]
	s_mov_b32 m0, s47
	v_readfirstlane_b32 s47, v7
	global_load_lds_dwordx4 v[8:9], off
	v_lshl_add_u64 v[4:5], v[4:5], 0, s[90:91]
	s_mov_b32 m0, s47
	v_lshl_add_u64 v[10:11], v[2:3], 0, s[16:17]
	global_load_lds_dwordx4 v[4:5], off
	v_add_u32_e32 v4, 0x6000, v100
	v_lshl_add_u64 v[2:3], v[2:3], 0, s[90:91]
	v_readfirstlane_b32 s47, v4
	v_add_u32_e32 v4, 0x7000, v100
	s_mov_b32 m0, s47
	v_readfirstlane_b32 s47, v4
	global_load_lds_dwordx4 v[10:11], off
	s_mov_b32 m0, s47
	s_lshl_b32 s44, s44, 13
	global_load_lds_dwordx4 v[2:3], off
	s_add_u32 s44, s44, 0x2000
	s_mul_i32 s50, s35, 0x360000
	s_mul_hi_u32 s51, s45, 0x48000
	s_mul_i32 s45, s45, 0x48000
	s_mul_hi_i32 s47, s35, 0x360000
	s_add_u32 s45, s50, s45
	s_addc_u32 s47, s47, s51
	s_add_u32 s45, s45, s46
	s_addc_u32 s47, s47, 0
	s_add_u32 s42, s42, s45
	s_addc_u32 s43, s43, s47
	v_lshl_add_u64 v[96:97], s[42:43], 0, v[0:1]
	s_mov_b64 s[50:51], s[42:43]
	s_mul_hi_i32 s42, s35, 0x48000
	s_mul_i32 s35, s35, 0x48000
	s_add_u32 s35, s35, s46
	s_addc_u32 s42, s42, 0
	s_lshl_b64 s[4:5], s[4:5], 7
	v_bitop3_b32 v2, v102, v12, 7 bitop3:0x78
	s_add_u32 s4, s35, s4
	v_lshlrev_b32_e32 v107, 4, v2
	v_bitop3_b32 v2, v102, v13, 2 bitop3:0x36
	s_addc_u32 s5, s42, s5
	v_lshlrev_b32_e32 v106, 4, v2
	v_bitop3_b32 v2, v102, v13, 4 bitop3:0x36
	s_add_u32 s4, s40, s4
	v_lshlrev_b32_e32 v103, 4, v2
	v_bitop3_b32 v2, v102, v13, 6 bitop3:0x36
	s_addc_u32 s5, s41, s5
	v_mov_b32_e32 v17, v16
	v_mov_b32_e32 v18, v16
	v_mov_b32_e32 v19, v16
	v_mov_b32_e32 v20, v16
	v_mov_b32_e32 v21, v16
	v_mov_b32_e32 v22, v16
	v_mov_b32_e32 v23, v16
	v_mov_b32_e32 v24, v16
	v_mov_b32_e32 v25, v16
	v_mov_b32_e32 v26, v16
	v_mov_b32_e32 v27, v16
	v_mov_b32_e32 v28, v16
	v_mov_b32_e32 v29, v16
	v_mov_b32_e32 v30, v16
	v_mov_b32_e32 v31, v16
	v_lshlrev_b32_e32 v101, 4, v2
	v_lshl_add_u64 v[98:99], s[4:5], 0, v[0:1]
	s_mov_b64 s[52:53], s[4:5]
	s_mov_b32 s35, 0
	s_mov_b64 s[4:5], 0
	v_mov_b32_e32 v0, 0
	v_mov_b32_e32 v1, v104
	v_mov_b32_e32 v2, v104
	v_mov_b32_e32 v3, v104
	v_mov_b32_e32 v4, v104
	v_mov_b32_e32 v5, v104
	v_mov_b32_e32 v7, v104
	v_mov_b32_e32 v8, v104
	v_mov_b32_e32 v9, v104
	v_mov_b32_e32 v10, v104
	v_mov_b32_e32 v11, v104
	v_mov_b32_e32 v12, v104
	v_mov_b32_e32 v13, v104
	v_subrev_u32_e32 v246, s52, v98
	v_add_u32_e32 v247, 0x1000, v246
	v_readfirstlane_b32 s43, v100
	s_add_u32 s52, s52, 0x4000
	s_addc_u32 s53, s53, 0
	s_add_u32 s50, s50, 0x4000
	s_addc_u32 s51, s51, 0
	v_add_u32_e32 v194, v108, v107
	v_add_u32_e32 v195, v108, v106
	v_add_u32_e32 v196, v108, v103
	v_add_u32_e32 v197, v108, v101
	s_waitcnt vmcnt(4)
	s_barrier
; template <int KIND>
; DI void attn_unit(const Params& p, int l, int b, int head, int qt, int qcol, int kcol, int vfeat, int gcol, int mixcol,
;                   int t1, int n1, int t2, int n2, char* smem) {
;     ...
;     for (int it = 0; it < nt; ++it) {
;         const int tile = (it < n1) ? t1 + it : t2 + (it - n1);
;         if (it + 1 < nt) asm volatile("s_waitcnt vmcnt(4)" ::: "memory"); else asm volatile("s_waitcnt vmcnt(0)" ::: "memory");
;         __builtin_amdgcn_s_barrier();
;         const char* sk = smem + sc * ATT_SLOT;
;         const char* sv = sk + ATT_V;
;         bool active = true;
;         if (KIND == 2 && tile < 32) active = (tile >= r0w) && (tile < r0w + 8);
;         bf16x8 kf[8], vf[8];
;         if (active) {
; #pragma unroll
;             for (int s = 0; s < 4; ++s)
; #pragma unroll
;                 for (int t = 0; t < 2; ++t) kf[2 * s + t] = *(const bf16x8*)(sk + (32 * t + r) * 128 + (((2 * s + h) ^ xr) << 4));
;         }
;         __builtin_amdgcn_sched_barrier(0);
;         if (it + 2 < nt) { const int nx = (it + 2 < n1) ? t1 + it + 2 : t2 + (it + 2 - n1); KV_ISSUE(nx, sn); }
;         sc = (sc == 2) ? 0 : sc + 1; sn = (sn == 2) ? 0 : sn + 1;
;         __builtin_amdgcn_sched_barrier(0);
;         if (active) {
;     ...
;             if (KIND == 0) {
;                 f32x16 S0[2], S1[2];
; #pragma unroll
;                 for (int t = 0; t < 2; ++t) { S0[t] = MFMA(kf[t], qf[0], cz); S1[t] = MFMA(kf[4 + t], qf[2], cz); }
; #pragma unroll
;                 for (int t = 0; t < 2; ++t) { S0[t] = MFMA(kf[2 + t], qf[1], S0[t]); S1[t] = MFMA(kf[6 + t], qf[3], S1[t]); }
;                 LOAD_VF();
;                 softmax_tile(S0, l0);
;                 pv_tile(S0, O0, vf);
;                 softmax_tile(S1, l1);
;                 pv_tile(S1, O1, vf);
;             } else {
;                 f32x16 S[2];
; #pragma unroll
;                 for (int t = 0; t < 2; ++t) S[t] = MFMA(kf[t], qf[0], cz);
; #pragma unroll
;                 for (int s = 1; s < 4; ++s)
; #pragma unroll
;                     for (int t = 0; t < 2; ++t) S[t] = MFMA(kf[2 * s + t], qf[s], S[t]);
;                 LOAD_VF();
;                 if (KIND == 2 && tile < 32) {
;                     const char* brow = smem + ATT_BIAS + (tile - nrow + 7) * 128;
; #pragma unroll
;                     for (int t = 0; t < 2; ++t)
; #pragma unroll
	ds_read_b128 v[144:147], v194
	ds_read_b128 v[148:151], v194 offset:4096
	ds_read_b128 v[152:155], v195
	ds_read_b128 v[156:159], v195 offset:4096
	ds_read_b128 v[160:163], v196
	ds_read_b128 v[164:167], v196 offset:4096
	ds_read_b128 v[168:171], v197
	ds_read_b128 v[172:175], v197 offset:4096
	s_lshl_b32 s42, s34, 14
	s_add_i32 s42, s42, s43
	s_mov_b32 m0, s42
	s_nop 0
	global_load_lds_dwordx4 v246, s[52:53]
	s_add_u32 m0, s42, 0x1000
	s_nop 0
	global_load_lds_dwordx4 v247, s[52:53]
	s_add_u32 m0, s42, 0x2000
	s_nop 0
	global_load_lds_dwordx4 v246, s[50:51]
	s_add_u32 m0, s42, 0x3000
	s_nop 0
	global_load_lds_dwordx4 v247, s[50:51]
	s_add_u32 s52, s52, 0x2000
	s_addc_u32 s53, s53, 0
	s_add_u32 s50, s50, 0x2000
	s_addc_u32 s51, s51, 0
	s_mov_b32 s4, 0x2000
	s_waitcnt lgkmcnt(0)
	v_mfma_f32_32x32x16_bf16 v[64:79], v[144:147], v[92:95], v[16:31]
	v_mfma_f32_32x32x16_bf16 v[48:63], v[148:151], v[92:95], v[16:31]
	v_mfma_f32_32x32x16_bf16 v[64:79], v[152:155], v[88:91], v[64:79]
	v_mfma_f32_32x32x16_bf16 v[48:63], v[156:159], v[88:91], v[48:63]
	v_mfma_f32_32x32x16_bf16 v[64:79], v[160:163], v[84:87], v[64:79]
	v_mfma_f32_32x32x16_bf16 v[48:63], v[164:167], v[84:87], v[48:63]
	v_mfma_f32_32x32x16_bf16 v[64:79], v[168:171], v[80:83], v[64:79]
	v_mfma_f32_32x32x16_bf16 v[48:63], v[172:175], v[80:83], v[48:63]
	ds_read_b128 v[110:113], v194 offset:8192
	ds_read_b128 v[114:117], v194 offset:12288
	ds_read_b128 v[118:121], v195 offset:8192
	ds_read_b128 v[122:125], v195 offset:12288
	ds_read_b128 v[126:129], v196 offset:8192
	ds_read_b128 v[130:133], v196 offset:12288
	ds_read_b128 v[134:137], v197 offset:8192
	ds_read_b128 v[138:141], v197 offset:12288
	s_mov_b32 s35, 1
	s_mov_b32 s34, 2
	v_lshl_add_u32 v198, s35, 14, v108
	v_add_u32_e32 v194, v198, v107
	v_add_u32_e32 v195, v198, v106
	v_add_u32_e32 v196, v198, v103
	v_add_u32_e32 v197, v198, v101
	s_waitcnt lgkmcnt(0)
	s_waitcnt vmcnt(4)
	s_barrier
	ds_read_b128 v[144:147], v194
	ds_read_b128 v[148:151], v194 offset:4096
	ds_read_b128 v[152:155], v195
	ds_read_b128 v[156:159], v195 offset:4096
	ds_read_b128 v[160:163], v196
	ds_read_b128 v[164:167], v196 offset:4096
	ds_read_b128 v[168:171], v197
	ds_read_b128 v[172:175], v197 offset:4096
	s_lshl_b32 s42, s75, 14
	s_add_i32 s42, s42, s43
	s_mov_b32 m0, s42
	s_nop 0
	global_load_lds_dwordx4 v246, s[52:53]
	s_add_u32 m0, s42, 0x1000
	s_nop 0
	global_load_lds_dwordx4 v247, s[52:53]
	s_add_u32 m0, s42, 0x2000
	s_nop 0
	global_load_lds_dwordx4 v246, s[50:51]
	s_add_u32 m0, s42, 0x3000
	s_nop 0
	global_load_lds_dwordx4 v247, s[50:51]
	s_add_u32 s52, s52, 0x2000
	s_addc_u32 s53, s53, 0
	s_add_u32 s50, s50, 0x2000
	s_addc_u32 s51, s51, 0
	v_exp_f32_e32 v214, v64
	v_exp_f32_e32 v215, v65
	v_exp_f32_e32 v216, v66
	v_exp_f32_e32 v217, v67
	v_exp_f32_e32 v218, v68
	v_exp_f32_e32 v219, v69
	v_exp_f32_e32 v220, v70
	v_exp_f32_e32 v221, v71
	v_exp_f32_e32 v222, v72
	v_exp_f32_e32 v223, v73
	v_exp_f32_e32 v224, v74
	v_exp_f32_e32 v225, v75
	v_exp_f32_e32 v226, v76
	v_exp_f32_e32 v227, v77
	v_exp_f32_e32 v228, v78
	v_exp_f32_e32 v229, v79
	v_exp_f32_e32 v230, v48
	v_exp_f32_e32 v231, v49
	v_exp_f32_e32 v232, v50
	v_exp_f32_e32 v233, v51
	v_exp_f32_e32 v234, v52
	v_exp_f32_e32 v235, v53
	v_exp_f32_e32 v236, v54
	v_exp_f32_e32 v237, v55
	v_exp_f32_e32 v238, v56
	v_exp_f32_e32 v239, v57
	v_exp_f32_e32 v240, v58
	v_exp_f32_e32 v241, v59
	v_exp_f32_e32 v242, v60
	v_exp_f32_e32 v243, v61
	v_exp_f32_e32 v244, v62
	v_exp_f32_e32 v245, v63
	v_add_u32_e32 v248, v108, v107
	v_add_u32_e32 v248, 0x8000, v248
	v_add_u32_e32 v249, v108, v106
	v_add_u32_e32 v249, 0x8000, v249
	v_add_u32_e32 v250, v108, v103
	v_add_u32_e32 v250, 0x8000, v250
	v_add_u32_e32 v251, v108, v101
	v_add_u32_e32 v251, 0x8000, v251
	v_add_u32_e32 v252, v108, v107
	v_add_u32_e32 v253, v108, v106
	v_add_u32_e32 v142, v108, v103
	v_add_u32_e32 v143, v108, v101
.LBB0_104:
	v_cvt_pk_bf16_f32 v176, v214, v215
	v_cvt_pk_bf16_f32 v177, v216, v217
	v_add_f32_e32 v199, v214, v216
	v_add_f32_e32 v192, v215, v217
	v_add_f32_e32 v199, v218, v199
	v_add_f32_e32 v192, v219, v192
	s_waitcnt lgkmcnt(0)
	v_mfma_f32_32x32x16_bf16 v[64:79], v[144:147], v[92:95], v[16:31]
	v_cvt_pk_bf16_f32 v178, v218, v219
	v_cvt_pk_bf16_f32 v179, v220, v221
	v_add_f32_e32 v199, v220, v199
	v_add_f32_e32 v192, v221, v192
	v_add_f32_e32 v199, v222, v199
	v_mfma_f32_32x32x16_bf16 v[48:63], v[148:151], v[92:95], v[16:31]
	v_add_f32_e32 v192, v223, v192
	v_cvt_pk_bf16_f32 v180, v222, v223
	v_cvt_pk_bf16_f32 v181, v224, v225
	v_add_f32_e32 v199, v224, v199
	v_add_f32_e32 v192, v225, v192
	v_mfma_f32_32x32x16_bf16 v[64:79], v[152:155], v[88:91], v[64:79]
	v_add_f32_e32 v199, v226, v199
	v_add_f32_e32 v192, v227, v192
	v_cvt_pk_bf16_f32 v182, v226, v227
	v_cvt_pk_bf16_f32 v183, v228, v229
	v_add_f32_e32 v199, v228, v199
	v_mfma_f32_32x32x16_bf16 v[48:63], v[156:159], v[88:91], v[48:63]
	v_add_f32_e32 v192, v229, v192
	v_add_f32_e32 v199, v230, v199
	v_add_f32_e32 v192, v231, v192
	v_cvt_pk_bf16_f32 v184, v230, v231
	v_cvt_pk_bf16_f32 v185, v232, v233
	v_mfma_f32_32x32x16_bf16 v[64:79], v[160:163], v[84:87], v[64:79]
	v_add_f32_e32 v199, v232, v199
	v_add_f32_e32 v192, v233, v192
	v_add_f32_e32 v199, v234, v199
	v_add_f32_e32 v192, v235, v192
	v_cvt_pk_bf16_f32 v186, v234, v235
	v_mfma_f32_32x32x16_bf16 v[48:63], v[164:167], v[84:87], v[48:63]
	v_cvt_pk_bf16_f32 v187, v236, v237
	v_add_f32_e32 v199, v236, v199
	v_add_f32_e32 v192, v237, v192
	v_add_f32_e32 v199, v238, v199
	v_add_f32_e32 v192, v239, v192
	v_mfma_f32_32x32x16_bf16 v[64:79], v[168:171], v[80:83], v[64:79]
	v_cvt_pk_bf16_f32 v188, v238, v239
	v_cvt_pk_bf16_f32 v189, v240, v241
; template <int KIND>
; DI void attn_unit(const Params& p, int l, int b, int head, int qt, int qcol, int kcol, int vfeat, int gcol, int mixcol,
;                   int t1, int n1, int t2, int n2, char* smem) {
;     ...
;     for (int it = 0; it < nt; ++it) {
;         const int tile = (it < n1) ? t1 + it : t2 + (it - n1);
;         if (it + 1 < nt) asm volatile("s_waitcnt vmcnt(4)" ::: "memory"); else asm volatile("s_waitcnt vmcnt(0)" ::: "memory");
;         __builtin_amdgcn_s_barrier();
;         const char* sk = smem + sc * ATT_SLOT;
;         const char* sv = sk + ATT_V;
;         bool active = true;
;         if (KIND == 2 && tile < 32) active = (tile >= r0w) && (tile < r0w + 8);
;         bf16x8 kf[8], vf[8];
;         if (active) {
; #pragma unroll
;             for (int s = 0; s < 4; ++s)
; #pragma unroll
;                 for (int t = 0; t < 2; ++t) kf[2 * s + t] = *(const bf16x8*)(sk + (32 * t + r) * 128 + (((2 * s + h) ^ xr) << 4));
;         }
;         __builtin_amdgcn_sched_barrier(0);
;         if (it + 2 < nt) { const int nx = (it + 2 < n1) ? t1 + it + 2 : t2 + (it + 2 - n1); KV_ISSUE(nx, sn); }
;         sc = (sc == 2) ? 0 : sc + 1; sn = (sn == 2) ? 0 : sn + 1;
;         __builtin_amdgcn_sched_barrier(0);
;         if (active) {
;     ...
;             if (KIND == 0) {
;                 f32x16 S0[2], S1[2];
; #pragma unroll
;                 for (int t = 0; t < 2; ++t) { S0[t] = MFMA(kf[t], qf[0], cz); S1[t] = MFMA(kf[4 + t], qf[2], cz); }
; #pragma unroll
;                 for (int t = 0; t < 2; ++t) { S0[t] = MFMA(kf[2 + t], qf[1], S0[t]); S1[t] = MFMA(kf[6 + t], qf[3], S1[t]); }
;                 LOAD_VF();
;                 softmax_tile(S0, l0);
;                 pv_tile(S0, O0, vf);
;                 softmax_tile(S1, l1);
;                 pv_tile(S1, O1, vf);
;             } else {
;                 f32x16 S[2];
; #pragma unroll
;                 for (int t = 0; t < 2; ++t) S[t] = MFMA(kf[t], qf[0], cz);
; #pragma unroll
;                 for (int s = 1; s < 4; ++s)
; #pragma unroll
;                     for (int t = 0; t < 2; ++t) S[t] = MFMA(kf[2 * s + t], qf[s], S[t]);
;                 LOAD_VF();
;                 if (KIND == 2 && tile < 32) {
;                     const char* brow = smem + ATT_BIAS + (tile - nrow + 7) * 128;
; #pragma unroll
;                     for (int t = 0; t < 2; ++t)
; #pragma unroll
	v_add_f32_e32 v199, v240, v199
	v_add_f32_e32 v192, v241, v192
	v_add_f32_e32 v199, v242, v199
	v_add_f32_e32 v192, v243, v192
	v_mfma_f32_32x32x16_bf16 v[48:63], v[172:175], v[80:83], v[48:63]
	v_cvt_pk_bf16_f32 v190, v242, v243
	v_cvt_pk_bf16_f32 v191, v244, v245
	v_add_f32_e32 v199, v244, v199
	v_add_f32_e32 v192, v245, v192
	v_add_f32_e32 v199, v199, v192
	v_add_f32_e32 v104, v104, v199
	v_mfma_f32_32x32x16_bf16 v[32:47], v[110:113], v[176:179], v[32:47]
	v_exp_f32_e32 v214, v64
	v_exp_f32_e32 v215, v65
	v_exp_f32_e32 v216, v66
	v_mfma_f32_32x32x16_bf16 v[0:15], v[114:117], v[176:179], v[0:15]
	v_exp_f32_e32 v217, v67
	v_exp_f32_e32 v218, v68
	v_exp_f32_e32 v219, v69
	ds_read_b128 v[110:113], v194 offset:8192
	ds_read_b128 v[114:117], v194 offset:12288
	v_mfma_f32_32x32x16_bf16 v[32:47], v[118:121], v[180:183], v[32:47]
	v_exp_f32_e32 v220, v70
	v_exp_f32_e32 v221, v71
	v_exp_f32_e32 v222, v72
	v_mfma_f32_32x32x16_bf16 v[0:15], v[122:125], v[180:183], v[0:15]
	v_exp_f32_e32 v223, v73
	v_exp_f32_e32 v224, v74
	v_exp_f32_e32 v225, v75
	ds_read_b128 v[118:121], v195 offset:8192
	ds_read_b128 v[122:125], v195 offset:12288
	v_mfma_f32_32x32x16_bf16 v[32:47], v[126:129], v[184:187], v[32:47]
	v_exp_f32_e32 v226, v76
	v_exp_f32_e32 v227, v77
	v_exp_f32_e32 v228, v78
	v_mfma_f32_32x32x16_bf16 v[0:15], v[130:133], v[184:187], v[0:15]
	v_exp_f32_e32 v229, v79
	v_exp_f32_e32 v230, v48
	v_exp_f32_e32 v231, v49
	ds_read_b128 v[126:129], v196 offset:8192
	ds_read_b128 v[130:133], v196 offset:12288
	v_mfma_f32_32x32x16_bf16 v[32:47], v[134:137], v[188:191], v[32:47]
	v_exp_f32_e32 v232, v50
	v_exp_f32_e32 v233, v51
	v_exp_f32_e32 v234, v52
	v_mfma_f32_32x32x16_bf16 v[0:15], v[138:141], v[188:191], v[0:15]
	v_exp_f32_e32 v235, v53
	v_exp_f32_e32 v236, v54
	v_exp_f32_e32 v237, v55
	ds_read_b128 v[134:137], v197 offset:8192
	ds_read_b128 v[138:141], v197 offset:12288
	s_add_u32 s4, s4, 0x2000
	s_addc_u32 s5, s5, 0
	s_cmp_eq_u32 s44, s4
	s_cbranch_scc1 .Lk1_drain
	v_exp_f32_e32 v238, v56
	v_exp_f32_e32 v239, v57
	v_exp_f32_e32 v240, v58
	v_exp_f32_e32 v241, v59
	s_lshl_b32 s42, s35, 14
	s_add_i32 s42, s42, s43
	s_waitcnt lgkmcnt(0)
	s_waitcnt vmcnt(4)
	s_barrier
	ds_read_b128 v[144:147], v248
	s_mov_b32 m0, s42
	ds_read_b128 v[148:151], v248 offset:4096
	global_load_lds_dwordx4 v246, s[52:53]
	v_exp_f32_e32 v242, v60
	ds_read_b128 v[152:155], v249
	s_add_u32 m0, s42, 0x1000
	ds_read_b128 v[156:159], v249 offset:4096
	global_load_lds_dwordx4 v247, s[52:53]
	v_exp_f32_e32 v243, v61
	ds_read_b128 v[160:163], v250
	s_add_u32 m0, s42, 0x2000
	ds_read_b128 v[164:167], v250 offset:4096
	global_load_lds_dwordx4 v246, s[50:51]
	v_exp_f32_e32 v244, v62
	ds_read_b128 v[168:171], v251
	s_add_u32 m0, s42, 0x3000
	ds_read_b128 v[172:175], v251 offset:4096
	global_load_lds_dwordx4 v247, s[50:51]
	v_exp_f32_e32 v245, v63
	s_add_u32 s52, s52, 0x2000
	s_addc_u32 s53, s53, 0
	s_add_u32 s50, s50, 0x2000
	s_addc_u32 s51, s51, 0
	s_mov_b32 s35, s34
	s_add_i32 s42, s34, 1
	s_cmp_lg_u32 s34, 2
	s_cselect_b32 s34, s42, 0
	v_cvt_pk_bf16_f32 v176, v214, v215
	v_cvt_pk_bf16_f32 v177, v216, v217
	v_add_f32_e32 v199, v214, v216
	v_add_f32_e32 v192, v215, v217
	v_add_f32_e32 v199, v218, v199
	v_add_f32_e32 v192, v219, v192
	s_waitcnt lgkmcnt(0)
	v_mfma_f32_32x32x16_bf16 v[64:79], v[144:147], v[92:95], v[16:31]
	v_cvt_pk_bf16_f32 v178, v218, v219
	v_cvt_pk_bf16_f32 v179, v220, v221
	v_add_f32_e32 v199, v220, v199
	v_add_f32_e32 v192, v221, v192
	v_add_f32_e32 v199, v222, v199
	v_mfma_f32_32x32x16_bf16 v[48:63], v[148:151], v[92:95], v[16:31]
	v_add_f32_e32 v192, v223, v192
	v_cvt_pk_bf16_f32 v180, v222, v223
	v_cvt_pk_bf16_f32 v181, v224, v225
	v_add_f32_e32 v199, v224, v199
	v_add_f32_e32 v192, v225, v192
	v_mfma_f32_32x32x16_bf16 v[64:79], v[152:155], v[88:91], v[64:79]
	v_add_f32_e32 v199, v226, v199
	v_add_f32_e32 v192, v227, v192
	v_cvt_pk_bf16_f32 v182, v226, v227
	v_cvt_pk_bf16_f32 v183, v228, v229
	v_add_f32_e32 v199, v228, v199
	v_mfma_f32_32x32x16_bf16 v[48:63], v[156:159], v[88:91], v[48:63]
	v_add_f32_e32 v192, v229, v192
	v_add_f32_e32 v199, v230, v199
	v_add_f32_e32 v192, v231, v192
	v_cvt_pk_bf16_f32 v184, v230, v231
	v_cvt_pk_bf16_f32 v185, v232, v233
	v_mfma_f32_32x32x16_bf16 v[64:79], v[160:163], v[84:87], v[64:79]
	v_add_f32_e32 v199, v232, v199
	v_add_f32_e32 v192, v233, v192
	v_add_f32_e32 v199, v234, v199
	v_add_f32_e32 v192, v235, v192
	v_cvt_pk_bf16_f32 v186, v234, v235
	v_mfma_f32_32x32x16_bf16 v[48:63], v[164:167], v[84:87], v[48:63]
	v_cvt_pk_bf16_f32 v187, v236, v237
	v_add_f32_e32 v199, v236, v199
	v_add_f32_e32 v192, v237, v192
	v_add_f32_e32 v199, v238, v199
	v_add_f32_e32 v192, v239, v192
	v_mfma_f32_32x32x16_bf16 v[64:79], v[168:171], v[80:83], v[64:79]
	v_cvt_pk_bf16_f32 v188, v238, v239
	v_cvt_pk_bf16_f32 v189, v240, v241
	v_add_f32_e32 v199, v240, v199
	v_add_f32_e32 v192, v241, v192
	v_add_f32_e32 v199, v242, v199
	v_add_f32_e32 v192, v243, v192
	v_mfma_f32_32x32x16_bf16 v[48:63], v[172:175], v[80:83], v[48:63]
	v_cvt_pk_bf16_f32 v190, v242, v243
	v_cvt_pk_bf16_f32 v191, v244, v245
	v_add_f32_e32 v199, v244, v199
	v_add_f32_e32 v192, v245, v192
	v_add_f32_e32 v199, v199, v192
	v_add_f32_e32 v104, v104, v199
	v_mfma_f32_32x32x16_bf16 v[32:47], v[110:113], v[176:179], v[32:47]
	v_exp_f32_e32 v214, v64
	v_exp_f32_e32 v215, v65
	v_exp_f32_e32 v216, v66
	v_mfma_f32_32x32x16_bf16 v[0:15], v[114:117], v[176:179], v[0:15]
	v_exp_f32_e32 v217, v67
	v_exp_f32_e32 v218, v68
	v_exp_f32_e32 v219, v69
	ds_read_b128 v[110:113], v248 offset:8192
	ds_read_b128 v[114:117], v248 offset:12288
	v_mfma_f32_32x32x16_bf16 v[32:47], v[118:121], v[180:183], v[32:47]
	v_exp_f32_e32 v220, v70
	v_exp_f32_e32 v221, v71
	v_exp_f32_e32 v222, v72
	v_mfma_f32_32x32x16_bf16 v[0:15], v[122:125], v[180:183], v[0:15]
	v_exp_f32_e32 v223, v73
	v_exp_f32_e32 v224, v74
	v_exp_f32_e32 v225, v75
	ds_read_b128 v[118:121], v249 offset:8192
	ds_read_b128 v[122:125], v249 offset:12288
	v_mfma_f32_32x32x16_bf16 v[32:47], v[126:129], v[184:187], v[32:47]
	v_exp_f32_e32 v226, v76
	v_exp_f32_e32 v227, v77
	v_exp_f32_e32 v228, v78
	v_mfma_f32_32x32x16_bf16 v[0:15], v[130:133], v[184:187], v[0:15]
	v_exp_f32_e32 v229, v79
	v_exp_f32_e32 v230, v48
	v_exp_f32_e32 v231, v49
	ds_read_b128 v[126:129], v250 offset:8192
	ds_read_b128 v[130:133], v250 offset:12288
	v_mfma_f32_32x32x16_bf16 v[32:47], v[134:137], v[188:191], v[32:47]
	v_exp_f32_e32 v232, v50
	v_exp_f32_e32 v233, v51
	v_exp_f32_e32 v234, v52
	v_mfma_f32_32x32x16_bf16 v[0:15], v[138:141], v[188:191], v[0:15]
	v_exp_f32_e32 v235, v53
	v_exp_f32_e32 v236, v54
	v_exp_f32_e32 v237, v55
	ds_read_b128 v[134:137], v251 offset:8192
	ds_read_b128 v[138:141], v251 offset:12288
	s_add_u32 s4, s4, 0x2000
	s_addc_u32 s5, s5, 0
	s_cmp_eq_u32 s44, s4
	s_cbranch_scc1 .Lk1_drain
; template <int KIND>
; DI void attn_unit(const Params& p, int l, int b, int head, int qt, int qcol, int kcol, int vfeat, int gcol, int mixcol,
;                   int t1, int n1, int t2, int n2, char* smem) {
;     ...
;     for (int it = 0; it < nt; ++it) {
;         const int tile = (it < n1) ? t1 + it : t2 + (it - n1);
;         if (it + 1 < nt) asm volatile("s_waitcnt vmcnt(4)" ::: "memory"); else asm volatile("s_waitcnt vmcnt(0)" ::: "memory");
;         __builtin_amdgcn_s_barrier();
;         const char* sk = smem + sc * ATT_SLOT;
;         const char* sv = sk + ATT_V;
;         bool active = true;
;         if (KIND == 2 && tile < 32) active = (tile >= r0w) && (tile < r0w + 8);
;         bf16x8 kf[8], vf[8];
;         if (active) {
; #pragma unroll
;             for (int s = 0; s < 4; ++s)
; #pragma unroll
;                 for (int t = 0; t < 2; ++t) kf[2 * s + t] = *(const bf16x8*)(sk + (32 * t + r) * 128 + (((2 * s + h) ^ xr) << 4));
;         }
;         __builtin_amdgcn_sched_barrier(0);
;         if (it + 2 < nt) { const int nx = (it + 2 < n1) ? t1 + it + 2 : t2 + (it + 2 - n1); KV_ISSUE(nx, sn); }
;         sc = (sc == 2) ? 0 : sc + 1; sn = (sn == 2) ? 0 : sn + 1;
;         __builtin_amdgcn_sched_barrier(0);
;         if (active) {
;     ...
;             if (KIND == 0) {
;                 f32x16 S0[2], S1[2];
; #pragma unroll
;                 for (int t = 0; t < 2; ++t) { S0[t] = MFMA(kf[t], qf[0], cz); S1[t] = MFMA(kf[4 + t], qf[2], cz); }
; #pragma unroll
;                 for (int t = 0; t < 2; ++t) { S0[t] = MFMA(kf[2 + t], qf[1], S0[t]); S1[t] = MFMA(kf[6 + t], qf[3], S1[t]); }
;                 LOAD_VF();
;                 softmax_tile(S0, l0);
;                 pv_tile(S0, O0, vf);
;                 softmax_tile(S1, l1);
;                 pv_tile(S1, O1, vf);
;             } else {
;                 f32x16 S[2];
; #pragma unroll
;                 for (int t = 0; t < 2; ++t) S[t] = MFMA(kf[t], qf[0], cz);
; #pragma unroll
;                 for (int s = 1; s < 4; ++s)
; #pragma unroll
;                     for (int t = 0; t < 2; ++t) S[t] = MFMA(kf[2 * s + t], qf[s], S[t]);
;                 LOAD_VF();
;                 if (KIND == 2 && tile < 32) {
;                     const char* brow = smem + ATT_BIAS + (tile - nrow + 7) * 128;
; #pragma unroll
;                     for (int t = 0; t < 2; ++t)
; #pragma unroll
	v_exp_f32_e32 v238, v56
	v_exp_f32_e32 v239, v57
	v_exp_f32_e32 v240, v58
	v_exp_f32_e32 v241, v59
	s_lshl_b32 s42, s35, 14
	s_add_i32 s42, s42, s43
	s_waitcnt lgkmcnt(0)
	s_waitcnt vmcnt(4)
	s_barrier
	ds_read_b128 v[144:147], v252
	s_mov_b32 m0, s42
	ds_read_b128 v[148:151], v252 offset:4096
	global_load_lds_dwordx4 v246, s[52:53]
	v_exp_f32_e32 v242, v60
	ds_read_b128 v[152:155], v253
	s_add_u32 m0, s42, 0x1000
	ds_read_b128 v[156:159], v253 offset:4096
	global_load_lds_dwordx4 v247, s[52:53]
	v_exp_f32_e32 v243, v61
	ds_read_b128 v[160:163], v142
	s_add_u32 m0, s42, 0x2000
	ds_read_b128 v[164:167], v142 offset:4096
	global_load_lds_dwordx4 v246, s[50:51]
	v_exp_f32_e32 v244, v62
	ds_read_b128 v[168:171], v143
	s_add_u32 m0, s42, 0x3000
	ds_read_b128 v[172:175], v143 offset:4096
	global_load_lds_dwordx4 v247, s[50:51]
	v_exp_f32_e32 v245, v63
	s_add_u32 s52, s52, 0x2000
	s_addc_u32 s53, s53, 0
	s_add_u32 s50, s50, 0x2000
	s_addc_u32 s51, s51, 0
	s_mov_b32 s35, s34
	s_add_i32 s42, s34, 1
	s_cmp_lg_u32 s34, 2
	s_cselect_b32 s34, s42, 0
	v_cvt_pk_bf16_f32 v176, v214, v215
	v_cvt_pk_bf16_f32 v177, v216, v217
	v_add_f32_e32 v199, v214, v216
	v_add_f32_e32 v192, v215, v217
	v_add_f32_e32 v199, v218, v199
	v_add_f32_e32 v192, v219, v192
	s_waitcnt lgkmcnt(0)
	v_mfma_f32_32x32x16_bf16 v[64:79], v[144:147], v[92:95], v[16:31]
	v_cvt_pk_bf16_f32 v178, v218, v219
	v_cvt_pk_bf16_f32 v179, v220, v221
	v_add_f32_e32 v199, v220, v199
	v_add_f32_e32 v192, v221, v192
	v_add_f32_e32 v199, v222, v199
	v_mfma_f32_32x32x16_bf16 v[48:63], v[148:151], v[92:95], v[16:31]
	v_add_f32_e32 v192, v223, v192
	v_cvt_pk_bf16_f32 v180, v222, v223
	v_cvt_pk_bf16_f32 v181, v224, v225
	v_add_f32_e32 v199, v224, v199
	v_add_f32_e32 v192, v225, v192
	v_mfma_f32_32x32x16_bf16 v[64:79], v[152:155], v[88:91], v[64:79]
	v_add_f32_e32 v199, v226, v199
	v_add_f32_e32 v192, v227, v192
	v_cvt_pk_bf16_f32 v182, v226, v227
	v_cvt_pk_bf16_f32 v183, v228, v229
	v_add_f32_e32 v199, v228, v199
	v_mfma_f32_32x32x16_bf16 v[48:63], v[156:159], v[88:91], v[48:63]
	v_add_f32_e32 v192, v229, v192
	v_add_f32_e32 v199, v230, v199
	v_add_f32_e32 v192, v231, v192
	v_cvt_pk_bf16_f32 v184, v230, v231
	v_cvt_pk_bf16_f32 v185, v232, v233
	v_mfma_f32_32x32x16_bf16 v[64:79], v[160:163], v[84:87], v[64:79]
	v_add_f32_e32 v199, v232, v199
	v_add_f32_e32 v192, v233, v192
	v_add_f32_e32 v199, v234, v199
	v_add_f32_e32 v192, v235, v192
	v_cvt_pk_bf16_f32 v186, v234, v235
	v_mfma_f32_32x32x16_bf16 v[48:63], v[164:167], v[84:87], v[48:63]
	v_cvt_pk_bf16_f32 v187, v236, v237
	v_add_f32_e32 v199, v236, v199
	v_add_f32_e32 v192, v237, v192
	v_add_f32_e32 v199, v238, v199
	v_add_f32_e32 v192, v239, v192
	v_mfma_f32_32x32x16_bf16 v[64:79], v[168:171], v[80:83], v[64:79]
	v_cvt_pk_bf16_f32 v188, v238, v239
	v_cvt_pk_bf16_f32 v189, v240, v241
	v_add_f32_e32 v199, v240, v199
	v_add_f32_e32 v192, v241, v192
	v_add_f32_e32 v199, v242, v199
	v_add_f32_e32 v192, v243, v192
	v_mfma_f32_32x32x16_bf16 v[48:63], v[172:175], v[80:83], v[48:63]
	v_cvt_pk_bf16_f32 v190, v242, v243
	v_cvt_pk_bf16_f32 v191, v244, v245
	v_add_f32_e32 v199, v244, v199
	v_add_f32_e32 v192, v245, v192
	v_add_f32_e32 v199, v199, v192
	v_add_f32_e32 v104, v104, v199
	v_mfma_f32_32x32x16_bf16 v[32:47], v[110:113], v[176:179], v[32:47]
	v_exp_f32_e32 v214, v64
	v_exp_f32_e32 v215, v65
	v_exp_f32_e32 v216, v66
	v_mfma_f32_32x32x16_bf16 v[0:15], v[114:117], v[176:179], v[0:15]
	v_exp_f32_e32 v217, v67
	v_exp_f32_e32 v218, v68
	v_exp_f32_e32 v219, v69
	ds_read_b128 v[110:113], v252 offset:8192
	ds_read_b128 v[114:117], v252 offset:12288
	v_mfma_f32_32x32x16_bf16 v[32:47], v[118:121], v[180:183], v[32:47]
	v_exp_f32_e32 v220, v70
	v_exp_f32_e32 v221, v71
	v_exp_f32_e32 v222, v72
	v_mfma_f32_32x32x16_bf16 v[0:15], v[122:125], v[180:183], v[0:15]
	v_exp_f32_e32 v223, v73
	v_exp_f32_e32 v224, v74
	v_exp_f32_e32 v225, v75
	ds_read_b128 v[118:121], v253 offset:8192
	ds_read_b128 v[122:125], v253 offset:12288
	v_mfma_f32_32x32x16_bf16 v[32:47], v[126:129], v[184:187], v[32:47]
	v_exp_f32_e32 v226, v76
	v_exp_f32_e32 v227, v77
	v_exp_f32_e32 v228, v78
	v_mfma_f32_32x32x16_bf16 v[0:15], v[130:133], v[184:187], v[0:15]
	v_exp_f32_e32 v229, v79
	v_exp_f32_e32 v230, v48
	v_exp_f32_e32 v231, v49
	ds_read_b128 v[126:129], v142 offset:8192
	ds_read_b128 v[130:133], v142 offset:12288
	v_mfma_f32_32x32x16_bf16 v[32:47], v[134:137], v[188:191], v[32:47]
	v_exp_f32_e32 v232, v50
	v_exp_f32_e32 v233, v51
	v_exp_f32_e32 v234, v52
	v_mfma_f32_32x32x16_bf16 v[0:15], v[138:141], v[188:191], v[0:15]
	v_exp_f32_e32 v235, v53
	v_exp_f32_e32 v236, v54
	v_exp_f32_e32 v237, v55
	ds_read_b128 v[134:137], v143 offset:8192
	ds_read_b128 v[138:141], v143 offset:12288
	s_add_u32 s4, s4, 0x2000
	s_addc_u32 s5, s5, 0
	s_cmp_eq_u32 s44, s4
	s_cbranch_scc1 .Lk1_drain
	v_exp_f32_e32 v238, v56
	v_exp_f32_e32 v239, v57
	v_exp_f32_e32 v240, v58
	v_exp_f32_e32 v241, v59
	s_lshl_b32 s42, s35, 14
	s_add_i32 s42, s42, s43
	s_waitcnt lgkmcnt(0)
	s_waitcnt vmcnt(4)
	s_barrier
	ds_read_b128 v[144:147], v194
	s_mov_b32 m0, s42
	ds_read_b128 v[148:151], v194 offset:4096
	global_load_lds_dwordx4 v246, s[52:53]
	v_exp_f32_e32 v242, v60
	ds_read_b128 v[152:155], v195
	s_add_u32 m0, s42, 0x1000
	ds_read_b128 v[156:159], v195 offset:4096
	global_load_lds_dwordx4 v247, s[52:53]
	v_exp_f32_e32 v243, v61
	ds_read_b128 v[160:163], v196
	s_add_u32 m0, s42, 0x2000
	ds_read_b128 v[164:167], v196 offset:4096
	global_load_lds_dwordx4 v246, s[50:51]
	v_exp_f32_e32 v244, v62
	ds_read_b128 v[168:171], v197
	s_add_u32 m0, s42, 0x3000
	ds_read_b128 v[172:175], v197 offset:4096
	global_load_lds_dwordx4 v247, s[50:51]
	v_exp_f32_e32 v245, v63
	s_add_u32 s52, s52, 0x2000
	s_addc_u32 s53, s53, 0
	s_add_u32 s50, s50, 0x2000
	s_addc_u32 s51, s51, 0
	s_mov_b32 s35, s34
	s_add_i32 s42, s34, 1
	s_cmp_lg_u32 s34, 2
	s_cselect_b32 s34, s42, 0
	s_branch .LBB0_104
